# k29 ordering with the loop-head compare used as the m0 wait-state filler (one s_nop fewer per iteration), reads still issued first
# baseline (speedup 1.0000x reference)
.Lprio_done:
	v_add_u32_e32 v170, 0x10000, v157
	ds_read_b128 v[128:131], v170
	ds_read_b128 v[132:135], v170 offset:1024
	ds_read_b128 v[136:139], v170 offset:2048
	ds_read_b128 v[140:143], v170 offset:3072
	ds_read_b128 v[166:169], v170 offset:16384
	ds_read_b128 v[176:179], v170 offset:17408
	ds_read_b128 v[180:183], v170 offset:18432
	ds_read_b128 v[184:187], v170 offset:19456
	s_add_i32 m0, s37, 0xc000
	ds_read_b128 v[188:191], v242
	ds_read_b128 v[192:195], v242 offset:1024
	ds_read_b128 v[196:199], v242 offset:2048
	ds_read_b128 v[200:203], v242 offset:3072
	ds_read_b128 v[204:207], v242 offset:4096
	ds_read_b128 v[208:211], v242 offset:5120
	ds_read_b128 v[212:215], v242 offset:6144
	ds_read_b128 v[216:219], v242 offset:7168
	s_add_u32 s0, s90, 0x80
	s_addc_u32 s1, s91, 0
	s_add_u32 s11, s2, 0x100
	s_addc_u32 s24, s3, 0
	s_mov_b32 s2, 0
	s_add_i32 s90, s2, 2
	s_add_u32 s82, s0, 0x80
	s_addc_u32 s3, s1, 0
	v_add_u32_e32 v232, s26, v150
	v_add_u32_e32 v233, s26, v154
	v_add_u32_e32 v234, s58, v148
	v_add_u32_e32 v235, s58, v152
	global_load_lds_dwordx4 v160, s[0:1]
	s_add_i32 m0, s37, 0xe000
	s_cmp_eq_u32 s62, s2
	global_load_lds_dwordx4 v162, s[0:1]
	s_cselect_b32 s3, s23, s3
	s_cselect_b32 s2, s22, s82
	s_cselect_b32 vcc_hi, s13, s24
	s_cselect_b32 vcc_lo, s12, s11
	s_waitcnt vmcnt(8) lgkmcnt(0)
	s_barrier
	v_mfma_f32_16x16x32_bf16 v[124:127], v[128:131], v[188:191], 0
	v_mfma_f32_16x16x32_bf16 v[120:123], v[136:139], v[188:191], 0
	v_mfma_f32_16x16x32_bf16 v[108:111], v[128:131], v[196:199], 0
	v_mfma_f32_16x16x32_bf16 v[104:107], v[136:139], v[196:199], 0
	v_mfma_f32_16x16x32_bf16 v[92:95], v[128:131], v[204:207], 0
	v_mfma_f32_16x16x32_bf16 v[88:91], v[136:139], v[204:207], 0
	v_mfma_f32_16x16x32_bf16 v[76:79], v[128:131], v[212:215], 0
	v_mfma_f32_16x16x32_bf16 v[72:75], v[136:139], v[212:215], 0
	v_mfma_f32_16x16x32_bf16 v[124:127], v[132:135], v[192:195], v[124:127]
	v_mfma_f32_16x16x32_bf16 v[120:123], v[140:143], v[192:195], v[120:123]
	v_mfma_f32_16x16x32_bf16 v[108:111], v[132:135], v[200:203], v[108:111]
	v_mfma_f32_16x16x32_bf16 v[104:107], v[140:143], v[200:203], v[104:107]
	v_mfma_f32_16x16x32_bf16 v[92:95], v[132:135], v[208:211], v[92:95]
	v_mfma_f32_16x16x32_bf16 v[88:91], v[140:143], v[208:211], v[88:91]
	v_mfma_f32_16x16x32_bf16 v[76:79], v[132:135], v[216:219], v[76:79]
	v_mfma_f32_16x16x32_bf16 v[72:75], v[140:143], v[216:219], v[72:75]
	v_mfma_f32_16x16x32_bf16 v[116:119], v[166:169], v[188:191], 0
	v_mfma_f32_16x16x32_bf16 v[112:115], v[180:183], v[188:191], 0
	v_mfma_f32_16x16x32_bf16 v[100:103], v[166:169], v[196:199], 0
	v_mfma_f32_16x16x32_bf16 v[96:99], v[180:183], v[196:199], 0
	v_mfma_f32_16x16x32_bf16 v[84:87], v[166:169], v[204:207], 0
	v_mfma_f32_16x16x32_bf16 v[80:83], v[180:183], v[204:207], 0
	v_mfma_f32_16x16x32_bf16 v[68:71], v[166:169], v[212:215], 0
	v_mfma_f32_16x16x32_bf16 v[64:67], v[180:183], v[212:215], 0
	v_mfma_f32_16x16x32_bf16 v[116:119], v[176:179], v[192:195], v[116:119]
	v_mfma_f32_16x16x32_bf16 v[112:115], v[184:187], v[192:195], v[112:115]
	v_mfma_f32_16x16x32_bf16 v[100:103], v[176:179], v[200:203], v[100:103]
	v_mfma_f32_16x16x32_bf16 v[96:99], v[184:187], v[200:203], v[96:99]
	v_mfma_f32_16x16x32_bf16 v[84:87], v[176:179], v[208:211], v[84:87]
	v_mfma_f32_16x16x32_bf16 v[80:83], v[184:187], v[208:211], v[80:83]
	v_mfma_f32_16x16x32_bf16 v[68:71], v[176:179], v[216:219], v[68:71]
	v_mfma_f32_16x16x32_bf16 v[64:67], v[184:187], v[216:219], v[64:67]
	s_barrier
	s_add_i32 m0, s36, 0x10000
	ds_read_b128 v[188:191], v242 offset:16384
	ds_read_b128 v[192:195], v242 offset:17408
	ds_read_b128 v[196:199], v242 offset:18432
	ds_read_b128 v[200:203], v242 offset:19456
	ds_read_b128 v[204:207], v242 offset:20480
	ds_read_b128 v[208:211], v242 offset:21504
	ds_read_b128 v[212:215], v242 offset:22528
	ds_read_b128 v[216:219], v242 offset:23552
	global_load_lds_dwordx4 v150, vcc
	s_add_i32 m0, s36, 0x12000
	s_nop 0
	global_load_lds_dwordx4 v154, vcc
	s_add_i32 m0, s36, 0x14000
	s_nop 0
	global_load_lds_dwordx4 v232, vcc
	s_add_i32 m0, s36, 0x16000
	s_nop 0
	global_load_lds_dwordx4 v233, vcc
	s_mov_b32 m0, s37
	s_nop 0
	global_load_lds_dwordx4 v148, s[2:3]
	s_mov_b32 m0, s42
	s_nop 0
	global_load_lds_dwordx4 v152, s[2:3]
	s_waitcnt vmcnt(8) lgkmcnt(0)
	s_barrier
	v_mfma_f32_16x16x32_bf16 v[60:63], v[128:131], v[188:191], 0
	v_mfma_f32_16x16x32_bf16 v[56:59], v[136:139], v[188:191], 0
	v_mfma_f32_16x16x32_bf16 v[44:47], v[128:131], v[196:199], 0
	v_mfma_f32_16x16x32_bf16 v[40:43], v[136:139], v[196:199], 0
	v_mfma_f32_16x16x32_bf16 v[28:31], v[128:131], v[204:207], 0
	v_mfma_f32_16x16x32_bf16 v[24:27], v[136:139], v[204:207], 0
	v_mfma_f32_16x16x32_bf16 v[12:15], v[128:131], v[212:215], 0
	v_mfma_f32_16x16x32_bf16 v[8:11], v[136:139], v[212:215], 0
	v_mfma_f32_16x16x32_bf16 v[60:63], v[132:135], v[192:195], v[60:63]
	v_mfma_f32_16x16x32_bf16 v[56:59], v[140:143], v[192:195], v[56:59]
	v_mfma_f32_16x16x32_bf16 v[44:47], v[132:135], v[200:203], v[44:47]
	v_mfma_f32_16x16x32_bf16 v[40:43], v[140:143], v[200:203], v[40:43]
	v_mfma_f32_16x16x32_bf16 v[28:31], v[132:135], v[208:211], v[28:31]
	v_mfma_f32_16x16x32_bf16 v[24:27], v[140:143], v[208:211], v[24:27]
	v_mfma_f32_16x16x32_bf16 v[12:15], v[132:135], v[216:219], v[12:15]
	v_mfma_f32_16x16x32_bf16 v[8:11], v[140:143], v[216:219], v[8:11]
	v_mfma_f32_16x16x32_bf16 v[52:55], v[166:169], v[188:191], 0
	v_mfma_f32_16x16x32_bf16 v[48:51], v[180:183], v[188:191], 0
	v_mfma_f32_16x16x32_bf16 v[36:39], v[166:169], v[196:199], 0
	v_mfma_f32_16x16x32_bf16 v[32:35], v[180:183], v[196:199], 0
	v_mfma_f32_16x16x32_bf16 v[20:23], v[166:169], v[204:207], 0
	v_mfma_f32_16x16x32_bf16 v[16:19], v[180:183], v[204:207], 0
	v_mfma_f32_16x16x32_bf16 v[4:7], v[166:169], v[212:215], 0
	v_mfma_f32_16x16x32_bf16 v[0:3], v[180:183], v[212:215], 0
	v_mfma_f32_16x16x32_bf16 v[52:55], v[176:179], v[192:195], v[52:55]
	v_mfma_f32_16x16x32_bf16 v[48:51], v[184:187], v[192:195], v[48:51]
	v_mfma_f32_16x16x32_bf16 v[36:39], v[176:179], v[200:203], v[36:39]
	v_mfma_f32_16x16x32_bf16 v[32:35], v[184:187], v[200:203], v[32:35]
	v_mfma_f32_16x16x32_bf16 v[20:23], v[176:179], v[208:211], v[20:23]
	v_mfma_f32_16x16x32_bf16 v[16:19], v[184:187], v[208:211], v[16:19]
	v_mfma_f32_16x16x32_bf16 v[4:7], v[176:179], v[216:219], v[4:7]
	v_mfma_f32_16x16x32_bf16 v[0:3], v[184:187], v[216:219], v[0:3]
	s_barrier
	ds_read_b128 v[128:131], v170 offset:32768
	ds_read_b128 v[132:135], v170 offset:33792
	ds_read_b128 v[136:139], v170 offset:34816
	ds_read_b128 v[140:143], v170 offset:35840
	ds_read_b128 v[166:169], v170 offset:49152
	ds_read_b128 v[176:179], v170 offset:50176
	ds_read_b128 v[180:183], v170 offset:51200
	ds_read_b128 v[184:187], v170 offset:52224
	s_mov_b32 m0, s43
	ds_read_b128 v[188:191], v242 offset:32768
	ds_read_b128 v[192:195], v242 offset:33792
	ds_read_b128 v[196:199], v242 offset:34816
	ds_read_b128 v[200:203], v242 offset:35840
	ds_read_b128 v[204:207], v242 offset:36864
	ds_read_b128 v[208:211], v242 offset:37888
	ds_read_b128 v[212:215], v242 offset:38912
	ds_read_b128 v[216:219], v242 offset:39936
	global_load_lds_dwordx4 v234, s[2:3]
	s_mov_b32 m0, s16
	s_nop 0
	global_load_lds_dwordx4 v235, s[2:3]
	s_waitcnt vmcnt(8) lgkmcnt(0)
	s_barrier
	v_mfma_f32_16x16x32_bf16 v[124:127], v[128:131], v[188:191], v[124:127]
	v_mfma_f32_16x16x32_bf16 v[120:123], v[136:139], v[188:191], v[120:123]
	v_mfma_f32_16x16x32_bf16 v[108:111], v[128:131], v[196:199], v[108:111]
	v_mfma_f32_16x16x32_bf16 v[104:107], v[136:139], v[196:199], v[104:107]
	v_mfma_f32_16x16x32_bf16 v[92:95], v[128:131], v[204:207], v[92:95]
	v_mfma_f32_16x16x32_bf16 v[88:91], v[136:139], v[204:207], v[88:91]
	v_mfma_f32_16x16x32_bf16 v[76:79], v[128:131], v[212:215], v[76:79]
	v_mfma_f32_16x16x32_bf16 v[72:75], v[136:139], v[212:215], v[72:75]
	v_mfma_f32_16x16x32_bf16 v[124:127], v[132:135], v[192:195], v[124:127]
	v_mfma_f32_16x16x32_bf16 v[120:123], v[140:143], v[192:195], v[120:123]
	v_mfma_f32_16x16x32_bf16 v[108:111], v[132:135], v[200:203], v[108:111]
	v_mfma_f32_16x16x32_bf16 v[104:107], v[140:143], v[200:203], v[104:107]
	v_mfma_f32_16x16x32_bf16 v[92:95], v[132:135], v[208:211], v[92:95]
	v_mfma_f32_16x16x32_bf16 v[88:91], v[140:143], v[208:211], v[88:91]
	v_mfma_f32_16x16x32_bf16 v[76:79], v[132:135], v[216:219], v[76:79]
	v_mfma_f32_16x16x32_bf16 v[72:75], v[140:143], v[216:219], v[72:75]
	v_mfma_f32_16x16x32_bf16 v[116:119], v[166:169], v[188:191], v[116:119]
	v_mfma_f32_16x16x32_bf16 v[112:115], v[180:183], v[188:191], v[112:115]
	v_mfma_f32_16x16x32_bf16 v[100:103], v[166:169], v[196:199], v[100:103]
	v_mfma_f32_16x16x32_bf16 v[96:99], v[180:183], v[196:199], v[96:99]
	v_mfma_f32_16x16x32_bf16 v[84:87], v[166:169], v[204:207], v[84:87]
	v_mfma_f32_16x16x32_bf16 v[80:83], v[180:183], v[204:207], v[80:83]
	v_mfma_f32_16x16x32_bf16 v[68:71], v[166:169], v[212:215], v[68:71]
	v_mfma_f32_16x16x32_bf16 v[64:67], v[180:183], v[212:215], v[64:67]
	v_mfma_f32_16x16x32_bf16 v[116:119], v[176:179], v[192:195], v[116:119]
	v_mfma_f32_16x16x32_bf16 v[112:115], v[184:187], v[192:195], v[112:115]
	v_mfma_f32_16x16x32_bf16 v[100:103], v[176:179], v[200:203], v[100:103]
	v_mfma_f32_16x16x32_bf16 v[96:99], v[184:187], v[200:203], v[96:99]
	v_mfma_f32_16x16x32_bf16 v[84:87], v[176:179], v[208:211], v[84:87]
	v_mfma_f32_16x16x32_bf16 v[80:83], v[184:187], v[208:211], v[80:83]
	v_mfma_f32_16x16x32_bf16 v[68:71], v[176:179], v[216:219], v[68:71]
	v_mfma_f32_16x16x32_bf16 v[64:67], v[184:187], v[216:219], v[64:67]
	s_barrier
	s_add_i32 m0, s36, 0x18000
	ds_read_b128 v[188:191], v242 offset:49152
	ds_read_b128 v[192:195], v242 offset:50176
	ds_read_b128 v[196:199], v242 offset:51200
	ds_read_b128 v[200:203], v242 offset:52224
	ds_read_b128 v[204:207], v242 offset:53248
	ds_read_b128 v[208:211], v242 offset:54272
	ds_read_b128 v[212:215], v242 offset:55296
	ds_read_b128 v[216:219], v242 offset:56320
	s_add_u32 vcc_lo, vcc_lo, 0x80
	s_addc_u32 vcc_hi, vcc_hi, 0
	global_load_lds_dwordx4 v150, vcc
	s_add_i32 m0, s36, 0x1a000
	s_add_u32 s2, s2, 0x80
	s_addc_u32 s3, s3, 0
	global_load_lds_dwordx4 v154, vcc
	s_add_i32 m0, s36, 0x1c000
	s_nop 0
	global_load_lds_dwordx4 v232, vcc
	s_add_i32 m0, s36, 0x1e000
	s_add_u32 s0, s0, 0x100
	s_addc_u32 s1, s1, 0
	global_load_lds_dwordx4 v233, vcc
	s_mov_b32 m0, s63
	s_add_u32 s11, s11, 0x100
	s_addc_u32 s24, s24, 0
	global_load_lds_dwordx4 v148, s[2:3]
	s_mov_b32 m0, s18
	s_nop 0
	global_load_lds_dwordx4 v152, s[2:3]
	s_waitcnt vmcnt(8) lgkmcnt(0)
	s_barrier
	v_mfma_f32_16x16x32_bf16 v[60:63], v[128:131], v[188:191], v[60:63]
	v_mfma_f32_16x16x32_bf16 v[56:59], v[136:139], v[188:191], v[56:59]
	v_mfma_f32_16x16x32_bf16 v[44:47], v[128:131], v[196:199], v[44:47]
	v_mfma_f32_16x16x32_bf16 v[40:43], v[136:139], v[196:199], v[40:43]
	v_mfma_f32_16x16x32_bf16 v[28:31], v[128:131], v[204:207], v[28:31]
	v_mfma_f32_16x16x32_bf16 v[24:27], v[136:139], v[204:207], v[24:27]
	v_mfma_f32_16x16x32_bf16 v[12:15], v[128:131], v[212:215], v[12:15]
	v_mfma_f32_16x16x32_bf16 v[8:11], v[136:139], v[212:215], v[8:11]
	v_mfma_f32_16x16x32_bf16 v[60:63], v[132:135], v[192:195], v[60:63]
	v_mfma_f32_16x16x32_bf16 v[56:59], v[140:143], v[192:195], v[56:59]
	v_mfma_f32_16x16x32_bf16 v[44:47], v[132:135], v[200:203], v[44:47]
	v_mfma_f32_16x16x32_bf16 v[40:43], v[140:143], v[200:203], v[40:43]
	v_mfma_f32_16x16x32_bf16 v[28:31], v[132:135], v[208:211], v[28:31]
	v_mfma_f32_16x16x32_bf16 v[24:27], v[140:143], v[208:211], v[24:27]
	v_mfma_f32_16x16x32_bf16 v[12:15], v[132:135], v[216:219], v[12:15]
	v_mfma_f32_16x16x32_bf16 v[8:11], v[140:143], v[216:219], v[8:11]
	v_mfma_f32_16x16x32_bf16 v[52:55], v[166:169], v[188:191], v[52:55]
	v_mfma_f32_16x16x32_bf16 v[48:51], v[180:183], v[188:191], v[48:51]
	v_mfma_f32_16x16x32_bf16 v[36:39], v[166:169], v[196:199], v[36:39]
	v_mfma_f32_16x16x32_bf16 v[32:35], v[180:183], v[196:199], v[32:35]
	v_mfma_f32_16x16x32_bf16 v[20:23], v[166:169], v[204:207], v[20:23]
	v_mfma_f32_16x16x32_bf16 v[16:19], v[180:183], v[204:207], v[16:19]
	v_mfma_f32_16x16x32_bf16 v[4:7], v[166:169], v[212:215], v[4:7]
	v_mfma_f32_16x16x32_bf16 v[0:3], v[180:183], v[212:215], v[0:3]
	v_mfma_f32_16x16x32_bf16 v[52:55], v[176:179], v[192:195], v[52:55]
	v_mfma_f32_16x16x32_bf16 v[48:51], v[184:187], v[192:195], v[48:51]
	v_mfma_f32_16x16x32_bf16 v[36:39], v[176:179], v[200:203], v[36:39]
	v_mfma_f32_16x16x32_bf16 v[32:35], v[184:187], v[200:203], v[32:35]
	v_mfma_f32_16x16x32_bf16 v[20:23], v[176:179], v[208:211], v[20:23]
	v_mfma_f32_16x16x32_bf16 v[16:19], v[184:187], v[208:211], v[16:19]
	v_mfma_f32_16x16x32_bf16 v[4:7], v[176:179], v[216:219], v[4:7]
	v_mfma_f32_16x16x32_bf16 v[0:3], v[184:187], v[216:219], v[0:3]
	s_barrier
	s_cmp_ge_u32 s90, s60
	s_mov_b32 s2, s90
	s_cbranch_scc1 .LBB0_297
.LBB0_295:
	ds_read_b128 v[128:131], v170
	ds_read_b128 v[132:135], v170 offset:1024
	ds_read_b128 v[136:139], v170 offset:2048
	ds_read_b128 v[140:143], v170 offset:3072
	ds_read_b128 v[166:169], v170 offset:16384
	ds_read_b128 v[176:179], v170 offset:17408
	ds_read_b128 v[180:183], v170 offset:18432
	ds_read_b128 v[184:187], v170 offset:19456
	s_add_i32 m0, s37, 0xc000
	ds_read_b128 v[188:191], v242
	ds_read_b128 v[192:195], v242 offset:1024
	ds_read_b128 v[196:199], v242 offset:2048
	ds_read_b128 v[200:203], v242 offset:3072
	ds_read_b128 v[204:207], v242 offset:4096
	ds_read_b128 v[208:211], v242 offset:5120
	ds_read_b128 v[212:215], v242 offset:6144
	ds_read_b128 v[216:219], v242 offset:7168
	s_add_i32 s90, s2, 2
	s_add_u32 s82, s0, 0x80
	s_addc_u32 s3, s1, 0
	global_load_lds_dwordx4 v160, s[0:1]
	s_add_i32 m0, s37, 0xe000
	s_cmp_eq_u32 s62, s2
	global_load_lds_dwordx4 v162, s[0:1]
	s_cselect_b32 s3, s23, s3
	s_cselect_b32 s2, s22, s82
	s_cselect_b32 vcc_hi, s13, s24
	s_cselect_b32 vcc_lo, s12, s11
	s_waitcnt vmcnt(8) lgkmcnt(0)
	s_barrier
	v_mfma_f32_16x16x32_bf16 v[124:127], v[128:131], v[188:191], v[124:127]
	v_mfma_f32_16x16x32_bf16 v[120:123], v[136:139], v[188:191], v[120:123]
	v_mfma_f32_16x16x32_bf16 v[108:111], v[128:131], v[196:199], v[108:111]
	v_mfma_f32_16x16x32_bf16 v[104:107], v[136:139], v[196:199], v[104:107]
	v_mfma_f32_16x16x32_bf16 v[92:95], v[128:131], v[204:207], v[92:95]
	v_mfma_f32_16x16x32_bf16 v[88:91], v[136:139], v[204:207], v[88:91]
	v_mfma_f32_16x16x32_bf16 v[76:79], v[128:131], v[212:215], v[76:79]
	v_mfma_f32_16x16x32_bf16 v[72:75], v[136:139], v[212:215], v[72:75]
	v_mfma_f32_16x16x32_bf16 v[124:127], v[132:135], v[192:195], v[124:127]
	v_mfma_f32_16x16x32_bf16 v[120:123], v[140:143], v[192:195], v[120:123]
	v_mfma_f32_16x16x32_bf16 v[108:111], v[132:135], v[200:203], v[108:111]
	v_mfma_f32_16x16x32_bf16 v[104:107], v[140:143], v[200:203], v[104:107]
	v_mfma_f32_16x16x32_bf16 v[92:95], v[132:135], v[208:211], v[92:95]
	v_mfma_f32_16x16x32_bf16 v[88:91], v[140:143], v[208:211], v[88:91]
	v_mfma_f32_16x16x32_bf16 v[76:79], v[132:135], v[216:219], v[76:79]
	v_mfma_f32_16x16x32_bf16 v[72:75], v[140:143], v[216:219], v[72:75]
	v_mfma_f32_16x16x32_bf16 v[116:119], v[166:169], v[188:191], v[116:119]
	v_mfma_f32_16x16x32_bf16 v[112:115], v[180:183], v[188:191], v[112:115]
	v_mfma_f32_16x16x32_bf16 v[100:103], v[166:169], v[196:199], v[100:103]
	v_mfma_f32_16x16x32_bf16 v[96:99], v[180:183], v[196:199], v[96:99]
	v_mfma_f32_16x16x32_bf16 v[84:87], v[166:169], v[204:207], v[84:87]
	v_mfma_f32_16x16x32_bf16 v[80:83], v[180:183], v[204:207], v[80:83]
	v_mfma_f32_16x16x32_bf16 v[68:71], v[166:169], v[212:215], v[68:71]
	v_mfma_f32_16x16x32_bf16 v[64:67], v[180:183], v[212:215], v[64:67]
	v_mfma_f32_16x16x32_bf16 v[116:119], v[176:179], v[192:195], v[116:119]
	v_mfma_f32_16x16x32_bf16 v[112:115], v[184:187], v[192:195], v[112:115]
	v_mfma_f32_16x16x32_bf16 v[100:103], v[176:179], v[200:203], v[100:103]
	v_mfma_f32_16x16x32_bf16 v[96:99], v[184:187], v[200:203], v[96:99]
	v_mfma_f32_16x16x32_bf16 v[84:87], v[176:179], v[208:211], v[84:87]
	v_mfma_f32_16x16x32_bf16 v[80:83], v[184:187], v[208:211], v[80:83]
	v_mfma_f32_16x16x32_bf16 v[68:71], v[176:179], v[216:219], v[68:71]
	v_mfma_f32_16x16x32_bf16 v[64:67], v[184:187], v[216:219], v[64:67]
	s_barrier
	s_add_i32 m0, s36, 0x10000
	ds_read_b128 v[188:191], v242 offset:16384
	ds_read_b128 v[192:195], v242 offset:17408
	ds_read_b128 v[196:199], v242 offset:18432
	ds_read_b128 v[200:203], v242 offset:19456
	ds_read_b128 v[204:207], v242 offset:20480
	ds_read_b128 v[208:211], v242 offset:21504
	ds_read_b128 v[212:215], v242 offset:22528
	ds_read_b128 v[216:219], v242 offset:23552
	global_load_lds_dwordx4 v150, vcc
	s_add_i32 m0, s36, 0x12000
	s_nop 0
	global_load_lds_dwordx4 v154, vcc
	s_add_i32 m0, s36, 0x14000
	s_nop 0
	global_load_lds_dwordx4 v232, vcc
	s_add_i32 m0, s36, 0x16000
	s_nop 0
	global_load_lds_dwordx4 v233, vcc
	s_mov_b32 m0, s37
	s_nop 0
	global_load_lds_dwordx4 v148, s[2:3]
	s_mov_b32 m0, s42
	s_nop 0
	global_load_lds_dwordx4 v152, s[2:3]
	s_waitcnt vmcnt(8) lgkmcnt(0)
	s_barrier
	v_mfma_f32_16x16x32_bf16 v[60:63], v[128:131], v[188:191], v[60:63]
	v_mfma_f32_16x16x32_bf16 v[56:59], v[136:139], v[188:191], v[56:59]
	v_mfma_f32_16x16x32_bf16 v[44:47], v[128:131], v[196:199], v[44:47]
	v_mfma_f32_16x16x32_bf16 v[40:43], v[136:139], v[196:199], v[40:43]
	v_mfma_f32_16x16x32_bf16 v[28:31], v[128:131], v[204:207], v[28:31]
	v_mfma_f32_16x16x32_bf16 v[24:27], v[136:139], v[204:207], v[24:27]
	v_mfma_f32_16x16x32_bf16 v[12:15], v[128:131], v[212:215], v[12:15]
	v_mfma_f32_16x16x32_bf16 v[8:11], v[136:139], v[212:215], v[8:11]
	v_mfma_f32_16x16x32_bf16 v[60:63], v[132:135], v[192:195], v[60:63]
	v_mfma_f32_16x16x32_bf16 v[56:59], v[140:143], v[192:195], v[56:59]
	v_mfma_f32_16x16x32_bf16 v[44:47], v[132:135], v[200:203], v[44:47]
	v_mfma_f32_16x16x32_bf16 v[40:43], v[140:143], v[200:203], v[40:43]
	v_mfma_f32_16x16x32_bf16 v[28:31], v[132:135], v[208:211], v[28:31]
	v_mfma_f32_16x16x32_bf16 v[24:27], v[140:143], v[208:211], v[24:27]
	v_mfma_f32_16x16x32_bf16 v[12:15], v[132:135], v[216:219], v[12:15]
	v_mfma_f32_16x16x32_bf16 v[8:11], v[140:143], v[216:219], v[8:11]
	v_mfma_f32_16x16x32_bf16 v[52:55], v[166:169], v[188:191], v[52:55]
	v_mfma_f32_16x16x32_bf16 v[48:51], v[180:183], v[188:191], v[48:51]
	v_mfma_f32_16x16x32_bf16 v[36:39], v[166:169], v[196:199], v[36:39]
	v_mfma_f32_16x16x32_bf16 v[32:35], v[180:183], v[196:199], v[32:35]
	v_mfma_f32_16x16x32_bf16 v[20:23], v[166:169], v[204:207], v[20:23]
	v_mfma_f32_16x16x32_bf16 v[16:19], v[180:183], v[204:207], v[16:19]
	v_mfma_f32_16x16x32_bf16 v[4:7], v[166:169], v[212:215], v[4:7]
	v_mfma_f32_16x16x32_bf16 v[0:3], v[180:183], v[212:215], v[0:3]
	v_mfma_f32_16x16x32_bf16 v[52:55], v[176:179], v[192:195], v[52:55]
	v_mfma_f32_16x16x32_bf16 v[48:51], v[184:187], v[192:195], v[48:51]
	v_mfma_f32_16x16x32_bf16 v[36:39], v[176:179], v[200:203], v[36:39]
	v_mfma_f32_16x16x32_bf16 v[32:35], v[184:187], v[200:203], v[32:35]
	v_mfma_f32_16x16x32_bf16 v[20:23], v[176:179], v[208:211], v[20:23]
	v_mfma_f32_16x16x32_bf16 v[16:19], v[184:187], v[208:211], v[16:19]
	v_mfma_f32_16x16x32_bf16 v[4:7], v[176:179], v[216:219], v[4:7]
	v_mfma_f32_16x16x32_bf16 v[0:3], v[184:187], v[216:219], v[0:3]
	s_barrier
	ds_read_b128 v[128:131], v170 offset:32768
	ds_read_b128 v[132:135], v170 offset:33792
	ds_read_b128 v[136:139], v170 offset:34816
	ds_read_b128 v[140:143], v170 offset:35840
	ds_read_b128 v[166:169], v170 offset:49152
	ds_read_b128 v[176:179], v170 offset:50176
	ds_read_b128 v[180:183], v170 offset:51200
	ds_read_b128 v[184:187], v170 offset:52224
	s_mov_b32 m0, s43
	ds_read_b128 v[188:191], v242 offset:32768
	ds_read_b128 v[192:195], v242 offset:33792
	ds_read_b128 v[196:199], v242 offset:34816
	ds_read_b128 v[200:203], v242 offset:35840
	ds_read_b128 v[204:207], v242 offset:36864
	ds_read_b128 v[208:211], v242 offset:37888
	ds_read_b128 v[212:215], v242 offset:38912
	ds_read_b128 v[216:219], v242 offset:39936
	global_load_lds_dwordx4 v234, s[2:3]
	s_mov_b32 m0, s16
	s_nop 0
	global_load_lds_dwordx4 v235, s[2:3]
	s_waitcnt vmcnt(8) lgkmcnt(0)
	s_barrier
	v_mfma_f32_16x16x32_bf16 v[124:127], v[128:131], v[188:191], v[124:127]
	v_mfma_f32_16x16x32_bf16 v[120:123], v[136:139], v[188:191], v[120:123]
	v_mfma_f32_16x16x32_bf16 v[108:111], v[128:131], v[196:199], v[108:111]
	v_mfma_f32_16x16x32_bf16 v[104:107], v[136:139], v[196:199], v[104:107]
	v_mfma_f32_16x16x32_bf16 v[92:95], v[128:131], v[204:207], v[92:95]
	v_mfma_f32_16x16x32_bf16 v[88:91], v[136:139], v[204:207], v[88:91]
	v_mfma_f32_16x16x32_bf16 v[76:79], v[128:131], v[212:215], v[76:79]
	v_mfma_f32_16x16x32_bf16 v[72:75], v[136:139], v[212:215], v[72:75]
	v_mfma_f32_16x16x32_bf16 v[124:127], v[132:135], v[192:195], v[124:127]
	v_mfma_f32_16x16x32_bf16 v[120:123], v[140:143], v[192:195], v[120:123]
	v_mfma_f32_16x16x32_bf16 v[108:111], v[132:135], v[200:203], v[108:111]
	v_mfma_f32_16x16x32_bf16 v[104:107], v[140:143], v[200:203], v[104:107]
	v_mfma_f32_16x16x32_bf16 v[92:95], v[132:135], v[208:211], v[92:95]
	v_mfma_f32_16x16x32_bf16 v[88:91], v[140:143], v[208:211], v[88:91]
	v_mfma_f32_16x16x32_bf16 v[76:79], v[132:135], v[216:219], v[76:79]
	v_mfma_f32_16x16x32_bf16 v[72:75], v[140:143], v[216:219], v[72:75]
	v_mfma_f32_16x16x32_bf16 v[116:119], v[166:169], v[188:191], v[116:119]
	v_mfma_f32_16x16x32_bf16 v[112:115], v[180:183], v[188:191], v[112:115]
	v_mfma_f32_16x16x32_bf16 v[100:103], v[166:169], v[196:199], v[100:103]
	v_mfma_f32_16x16x32_bf16 v[96:99], v[180:183], v[196:199], v[96:99]
	v_mfma_f32_16x16x32_bf16 v[84:87], v[166:169], v[204:207], v[84:87]
	v_mfma_f32_16x16x32_bf16 v[80:83], v[180:183], v[204:207], v[80:83]
	v_mfma_f32_16x16x32_bf16 v[68:71], v[166:169], v[212:215], v[68:71]
	v_mfma_f32_16x16x32_bf16 v[64:67], v[180:183], v[212:215], v[64:67]
	v_mfma_f32_16x16x32_bf16 v[116:119], v[176:179], v[192:195], v[116:119]
	v_mfma_f32_16x16x32_bf16 v[112:115], v[184:187], v[192:195], v[112:115]
	v_mfma_f32_16x16x32_bf16 v[100:103], v[176:179], v[200:203], v[100:103]
	v_mfma_f32_16x16x32_bf16 v[96:99], v[184:187], v[200:203], v[96:99]
	v_mfma_f32_16x16x32_bf16 v[84:87], v[176:179], v[208:211], v[84:87]
	v_mfma_f32_16x16x32_bf16 v[80:83], v[184:187], v[208:211], v[80:83]
	v_mfma_f32_16x16x32_bf16 v[68:71], v[176:179], v[216:219], v[68:71]
	v_mfma_f32_16x16x32_bf16 v[64:67], v[184:187], v[216:219], v[64:67]
	s_barrier
	s_add_i32 m0, s36, 0x18000
	ds_read_b128 v[188:191], v242 offset:49152
	ds_read_b128 v[192:195], v242 offset:50176
	ds_read_b128 v[196:199], v242 offset:51200
	ds_read_b128 v[200:203], v242 offset:52224
	ds_read_b128 v[204:207], v242 offset:53248
	ds_read_b128 v[208:211], v242 offset:54272
	ds_read_b128 v[212:215], v242 offset:55296
	ds_read_b128 v[216:219], v242 offset:56320
	s_add_u32 vcc_lo, vcc_lo, 0x80
	s_addc_u32 vcc_hi, vcc_hi, 0
	global_load_lds_dwordx4 v150, vcc
	s_add_i32 m0, s36, 0x1a000
	s_add_u32 s2, s2, 0x80
	s_addc_u32 s3, s3, 0
	global_load_lds_dwordx4 v154, vcc
	s_add_i32 m0, s36, 0x1c000
	s_nop 0
	global_load_lds_dwordx4 v232, vcc
	s_add_i32 m0, s36, 0x1e000
	s_add_u32 s0, s0, 0x100
	s_addc_u32 s1, s1, 0
	global_load_lds_dwordx4 v233, vcc
	s_mov_b32 m0, s63
	s_add_u32 s11, s11, 0x100
	s_addc_u32 s24, s24, 0
	global_load_lds_dwordx4 v148, s[2:3]
	s_mov_b32 m0, s18
	s_nop 0
	global_load_lds_dwordx4 v152, s[2:3]
	s_waitcnt vmcnt(8) lgkmcnt(0)
	s_barrier
	v_mfma_f32_16x16x32_bf16 v[60:63], v[128:131], v[188:191], v[60:63]
	v_mfma_f32_16x16x32_bf16 v[56:59], v[136:139], v[188:191], v[56:59]
	v_mfma_f32_16x16x32_bf16 v[44:47], v[128:131], v[196:199], v[44:47]
	v_mfma_f32_16x16x32_bf16 v[40:43], v[136:139], v[196:199], v[40:43]
	v_mfma_f32_16x16x32_bf16 v[28:31], v[128:131], v[204:207], v[28:31]
	v_mfma_f32_16x16x32_bf16 v[24:27], v[136:139], v[204:207], v[24:27]
	v_mfma_f32_16x16x32_bf16 v[12:15], v[128:131], v[212:215], v[12:15]
	v_mfma_f32_16x16x32_bf16 v[8:11], v[136:139], v[212:215], v[8:11]
	v_mfma_f32_16x16x32_bf16 v[60:63], v[132:135], v[192:195], v[60:63]
	v_mfma_f32_16x16x32_bf16 v[56:59], v[140:143], v[192:195], v[56:59]
	v_mfma_f32_16x16x32_bf16 v[44:47], v[132:135], v[200:203], v[44:47]
	v_mfma_f32_16x16x32_bf16 v[40:43], v[140:143], v[200:203], v[40:43]
	v_mfma_f32_16x16x32_bf16 v[28:31], v[132:135], v[208:211], v[28:31]
	v_mfma_f32_16x16x32_bf16 v[24:27], v[140:143], v[208:211], v[24:27]
	v_mfma_f32_16x16x32_bf16 v[12:15], v[132:135], v[216:219], v[12:15]
	v_mfma_f32_16x16x32_bf16 v[8:11], v[140:143], v[216:219], v[8:11]
	v_mfma_f32_16x16x32_bf16 v[52:55], v[166:169], v[188:191], v[52:55]
	v_mfma_f32_16x16x32_bf16 v[48:51], v[180:183], v[188:191], v[48:51]
	v_mfma_f32_16x16x32_bf16 v[36:39], v[166:169], v[196:199], v[36:39]
	v_mfma_f32_16x16x32_bf16 v[32:35], v[180:183], v[196:199], v[32:35]
	v_mfma_f32_16x16x32_bf16 v[20:23], v[166:169], v[204:207], v[20:23]
	v_mfma_f32_16x16x32_bf16 v[16:19], v[180:183], v[204:207], v[16:19]
	v_mfma_f32_16x16x32_bf16 v[4:7], v[166:169], v[212:215], v[4:7]
	v_mfma_f32_16x16x32_bf16 v[0:3], v[180:183], v[212:215], v[0:3]
	v_mfma_f32_16x16x32_bf16 v[52:55], v[176:179], v[192:195], v[52:55]
	v_mfma_f32_16x16x32_bf16 v[48:51], v[184:187], v[192:195], v[48:51]
	v_mfma_f32_16x16x32_bf16 v[36:39], v[176:179], v[200:203], v[36:39]
	v_mfma_f32_16x16x32_bf16 v[32:35], v[184:187], v[200:203], v[32:35]
	v_mfma_f32_16x16x32_bf16 v[20:23], v[176:179], v[208:211], v[20:23]
	v_mfma_f32_16x16x32_bf16 v[16:19], v[184:187], v[208:211], v[16:19]
	v_mfma_f32_16x16x32_bf16 v[4:7], v[176:179], v[216:219], v[4:7]
	v_mfma_f32_16x16x32_bf16 v[0:3], v[184:187], v[216:219], v[0:3]
	s_barrier
	s_cmp_ge_u32 s90, s60
	s_mov_b32 s2, s90
	s_cbranch_scc0 .LBB0_295
	s_branch .LBB0_297
